# grid barrier: each workgroup's leader lane invalidates the CU L1 right after its arrival atomic (the CU issues no L1 loads while it waits) instead of after the release is observed
# baseline (speedup 1.0000x reference)
; __device__ __forceinline__ unsigned xb_add(unsigned* p, unsigned v) { return __hip_atomic_fetch_add(p, v, __ATOMIC_RELAXED, __HIP_MEMORY_SCOPE_AGENT); }
; __device__ __forceinline__ void xcd_barrier(const XcdBarrier& b) {
;     ...
;     if (threadIdx.x == 0) {
;         unsigned* bar = b.bar;
;         __builtin_amdgcn_s_waitcnt(0);
;         unsigned nloc = b.st[0], nx = b.st[1];
;         if (nloc == 0u) { xcd_barrier_complete(bar, b.x, nloc, nx); b.st[0] = nloc; b.st[1] = nx; }
;         const unsigned old = xb_add(&bar[XB_XSUB(b.x)], 1u);
.LBB0_109:
	s_mov_b64 s[8:9], exec
	v_readlane_b32 s6, v254, 4
	s_lshl_b32 s6, s6, 8
	v_readlane_b32 s10, v254, 2
	v_mbcnt_lo_u32_b32 v1, s8, 0
	v_readlane_b32 s11, v254, 3
	s_add_u32 s6, s10, s6
	v_mbcnt_hi_u32_b32 v1, s9, v1
	s_addc_u32 s7, s11, 0
	v_cmp_eq_u32_e32 vcc, 0, v1
	s_and_saveexec_b64 s[10:11], vcc
	s_cbranch_execz .LBB0_111
	s_bcnt1_i32_b64 s8, s[8:9]
	v_mov_b32_e32 v3, 0x1000
	v_mov_b32_e32 v4, s8
	global_atomic_add v3, v3, v4, s[6:7] offset:1024 sc0
	buffer_inv sc1

; __device__ __forceinline__ unsigned xb_ld(unsigned* p)              { return __hip_atomic_load(p, __ATOMIC_RELAXED, __HIP_MEMORY_SCOPE_AGENT); }
; #define XB_SPIN(cond, bar) do { unsigned _sp = 0; while (cond) { __builtin_amdgcn_s_sleep(1); \
;     if ((++_sp & 255u) == 0u) { if (xb_ld(&(bar)[XB_TMO])) break; if (_sp > XB_SPIN_CAP) { atomicAdd(&(bar)[XB_TMO], 1u); break; } } } } while (0)
; __device__ __forceinline__ void xcd_barrier(const XcdBarrier& b) {
;     ...
;         } else {
;             XB_SPIN(xb_ld(&bar[XB_XGEN(b.x)]) == gen, bar);
;             __builtin_amdgcn_fence(__ATOMIC_ACQUIRE, "agent");
;             asm volatile("s_waitcnt vmcnt(0)" ::: "memory");
;         }
.LBB0_124:
	s_or_b64 exec, exec, s[10:11]
	s_waitcnt vmcnt(0)
	s_waitcnt vmcnt(0)

; __device__ __forceinline__ unsigned xb_add(unsigned* p, unsigned v) { return __hip_atomic_fetch_add(p, v, __ATOMIC_RELAXED, __HIP_MEMORY_SCOPE_AGENT); }
; __device__ __forceinline__ void xcd_barrier(const XcdBarrier& b) {
;     ...
;             __builtin_amdgcn_fence(__ATOMIC_ACQUIRE, "agent");
;             xb_add(&bar[XB_XGEN(b.x)], 1u);
;             asm volatile("s_waitcnt vmcnt(0)" ::: "memory");
.LBB0_142:
	s_or_b64 exec, exec, s[8:9]
	s_mov_b64 s[8:9], exec
	v_mbcnt_lo_u32_b32 v0, s8, 0
	v_mbcnt_hi_u32_b32 v0, s9, v0
	v_cmp_eq_u32_e32 vcc, 0, v0
	s_waitcnt vmcnt(0)
	s_and_saveexec_b64 s[10:11], vcc
	s_cbranch_execz .LBB0_144
	s_bcnt1_i32_b64 s8, s[8:9]
	v_mov_b32_e32 v0, 0x2000
	v_mov_b32_e32 v1, s8
	global_atomic_add v0, v1, s[6:7] offset:1024

; __device__ __forceinline__ unsigned xb_add(unsigned* p, unsigned v) { return __hip_atomic_fetch_add(p, v, __ATOMIC_RELAXED, __HIP_MEMORY_SCOPE_AGENT); }
; __device__ __forceinline__ void xcd_barrier(const XcdBarrier& b) {
;     ...
;     if (threadIdx.x == 0) {
;         unsigned* bar = b.bar;
;         __builtin_amdgcn_s_waitcnt(0);
;         unsigned nloc = b.st[0], nx = b.st[1];
;         if (nloc == 0u) { xcd_barrier_complete(bar, b.x, nloc, nx); b.st[0] = nloc; b.st[1] = nx; }
;         const unsigned old = xb_add(&bar[XB_XSUB(b.x)], 1u);
.LBB0_188:
	s_mov_b64 s[6:7], exec
	v_readlane_b32 s4, v254, 4
	s_lshl_b32 s4, s4, 8
	v_readlane_b32 s8, v254, 2
	v_mbcnt_lo_u32_b32 v1, s6, 0
	v_readlane_b32 s9, v254, 3
	s_add_u32 s4, s8, s4
	v_mbcnt_hi_u32_b32 v1, s7, v1
	s_addc_u32 s5, s9, 0
	v_cmp_eq_u32_e32 vcc, 0, v1
	s_and_saveexec_b64 s[8:9], vcc
	s_cbranch_execz .LBB0_190
	s_bcnt1_i32_b64 s6, s[6:7]
	v_mov_b32_e32 v3, 0x1000
	v_mov_b32_e32 v4, s6
	global_atomic_add v3, v3, v4, s[4:5] offset:1024 sc0
	buffer_inv sc1

; __device__ __forceinline__ unsigned xb_ld(unsigned* p)              { return __hip_atomic_load(p, __ATOMIC_RELAXED, __HIP_MEMORY_SCOPE_AGENT); }
; #define XB_SPIN(cond, bar) do { unsigned _sp = 0; while (cond) { __builtin_amdgcn_s_sleep(1); \
;     if ((++_sp & 255u) == 0u) { if (xb_ld(&(bar)[XB_TMO])) break; if (_sp > XB_SPIN_CAP) { atomicAdd(&(bar)[XB_TMO], 1u); break; } } } } while (0)
; __device__ __forceinline__ void xcd_barrier(const XcdBarrier& b) {
;     ...
;         } else {
;             XB_SPIN(xb_ld(&bar[XB_XGEN(b.x)]) == gen, bar);
;             __builtin_amdgcn_fence(__ATOMIC_ACQUIRE, "agent");
;             asm volatile("s_waitcnt vmcnt(0)" ::: "memory");
;         }
.LBB0_203:
	s_or_b64 exec, exec, s[8:9]
	s_waitcnt vmcnt(0)
	s_waitcnt vmcnt(0)

; __device__ __forceinline__ unsigned xb_add(unsigned* p, unsigned v) { return __hip_atomic_fetch_add(p, v, __ATOMIC_RELAXED, __HIP_MEMORY_SCOPE_AGENT); }
; __device__ __forceinline__ void xcd_barrier(const XcdBarrier& b) {
;     ...
;             __builtin_amdgcn_fence(__ATOMIC_ACQUIRE, "agent");
;             xb_add(&bar[XB_XGEN(b.x)], 1u);
;             asm volatile("s_waitcnt vmcnt(0)" ::: "memory");
.LBB0_221:
	s_or_b64 exec, exec, s[6:7]
	s_mov_b64 s[6:7], exec
	v_mbcnt_lo_u32_b32 v0, s6, 0
	v_mbcnt_hi_u32_b32 v0, s7, v0
	v_cmp_eq_u32_e32 vcc, 0, v0
	s_waitcnt vmcnt(0)
	s_and_saveexec_b64 s[8:9], vcc
	s_cbranch_execz .LBB0_223
	s_bcnt1_i32_b64 s6, s[6:7]
	v_mov_b32_e32 v0, 0x2000
	v_mov_b32_e32 v1, s6
	global_atomic_add v0, v1, s[4:5] offset:1024
